# attention epilogue: the 64 lane^1 exchanges use a DPP quad_perm move instead of ds_bpermute (on top of the pipelined final norm)
# baseline (speedup 1.0000x reference)
.LBB0_1245:
	s_mov_b32 s11, s87
	s_mov_b32 s33, s77
	s_mov_b64 s[0:1], exec
	v_readlane_b32 s2, v243, 48
	v_readlane_b32 s3, v243, 49
	s_and_b64 s[2:3], s[0:1], s[2:3]
	s_mov_b64 exec, s[2:3]
	ds_write_b32 v181, v64
	s_or_b64 exec, exec, s[0:1]
	v_mov_b32_e32 v64, v182
	s_waitcnt lgkmcnt(0)
	ds_read_b32 v65, v183
	v_and_b32_e32 v67, 64, v179
	v_add_u32_e32 v68, 64, v67
	v_xor_b32_e32 v66, 1, v179
	v_cmp_lt_i32_e32 vcc, v66, v68
	s_waitcnt lgkmcnt(0)
	v_rcp_f32_e32 v67, v65
	s_lshl_b32 s0, s53, 20
	v_cndmask_b32_e32 v65, v179, v66, vcc
	s_add_u32 s0, s49, s0
	v_lshlrev_b32_e32 v66, 2, v65
	v_mul_f32_e32 v48, v48, v67
	s_addc_u32 s1, s50, 0
	s_lshl_b32 s2, s52, 8
	s_nop 1
	v_mov_b32_dpp v68, v48 quad_perm:[1,0,3,2] row_mask:0xf bank_mask:0xf
	s_and_b32 s2, s2, 0xf00
	s_add_u32 s0, s0, s2
	s_addc_u32 s1, s1, 0
	v_mov_b32_e32 v65, v165
	v_lshl_add_u64 v[64:65], v[64:65], 1, s[0:1]
	s_and_saveexec_b64 s[0:1], s[4:5]
	s_cbranch_execz .LBB0_1249
	s_waitcnt lgkmcnt(0)
	v_cvt_pk_bf16_f32 v48, v48, v68
	global_store_dword v[64:65], v48, off
.LBB0_1249:
	s_or_b64 exec, exec, s[0:1]
	v_mul_f32_e32 v32, v32, v67
	s_nop 1
	v_mov_b32_dpp v48, v32 quad_perm:[1,0,3,2] row_mask:0xf bank_mask:0xf
	s_and_saveexec_b64 s[0:1], s[4:5]
	s_cbranch_execz .LBB0_1251
	s_waitcnt lgkmcnt(0)
	v_cvt_pk_bf16_f32 v32, v32, v48
	global_store_dword v[64:65], v32, off offset:64
.LBB0_1251:
	s_or_b64 exec, exec, s[0:1]
	v_mul_f32_e32 v16, v16, v67
	s_nop 1
	v_mov_b32_dpp v32, v16 quad_perm:[1,0,3,2] row_mask:0xf bank_mask:0xf
	s_and_saveexec_b64 s[0:1], s[4:5]
	s_cbranch_execz .LBB0_1253
	s_waitcnt lgkmcnt(0)
	v_cvt_pk_bf16_f32 v16, v16, v32
	global_store_dword v[64:65], v16, off offset:128
.LBB0_1253:
	s_or_b64 exec, exec, s[0:1]
	v_mul_f32_e32 v0, v0, v67
	s_nop 1
	v_mov_b32_dpp v16, v0 quad_perm:[1,0,3,2] row_mask:0xf bank_mask:0xf
	s_and_saveexec_b64 s[0:1], s[4:5]
	s_cbranch_execz .LBB0_1255
	s_waitcnt lgkmcnt(0)
	v_cvt_pk_bf16_f32 v0, v0, v16
	global_store_dword v[64:65], v0, off offset:192
.LBB0_1255:
	s_or_b64 exec, exec, s[0:1]
	ds_read_b32 v0, v183 offset:4
	s_waitcnt lgkmcnt(0)
	v_rcp_f32_e32 v0, v0
	s_nop 0
	v_mul_f32_e32 v16, v49, v0
	s_nop 1
	v_mov_b32_dpp v32, v16 quad_perm:[1,0,3,2] row_mask:0xf bank_mask:0xf
	s_and_saveexec_b64 s[0:1], s[4:5]
	s_cbranch_execz .LBB0_1257
	v_add_co_u32_e32 v48, vcc, 0x1000, v64
	s_waitcnt lgkmcnt(0)
	v_cvt_pk_bf16_f32 v16, v16, v32
	s_nop 0
	v_addc_co_u32_e32 v49, vcc, 0, v65, vcc
	global_store_dword v[48:49], v16, off
.LBB0_1257:
	s_or_b64 exec, exec, s[0:1]
	v_mul_f32_e32 v16, v33, v0
	s_waitcnt lgkmcnt(0)
	s_nop 1
	v_mov_b32_dpp v32, v16 quad_perm:[1,0,3,2] row_mask:0xf bank_mask:0xf
	s_and_saveexec_b64 s[0:1], s[4:5]
	s_cbranch_execz .LBB0_1259
	s_waitcnt lgkmcnt(0)
	v_cvt_pk_bf16_f32 v16, v16, v32
	v_add_co_u32_e32 v32, vcc, 0x1000, v64
	s_nop 1
	v_addc_co_u32_e32 v33, vcc, 0, v65, vcc
	global_store_dword v[32:33], v16, off offset:64
.LBB0_1259:
	s_or_b64 exec, exec, s[0:1]
	v_mul_f32_e32 v16, v17, v0
	s_nop 1
	v_mov_b32_dpp v17, v16 quad_perm:[1,0,3,2] row_mask:0xf bank_mask:0xf
	s_and_saveexec_b64 s[0:1], s[4:5]
	s_cbranch_execz .LBB0_1261
	s_waitcnt lgkmcnt(0)
	v_cvt_pk_bf16_f32 v32, v16, v17
	v_add_co_u32_e32 v16, vcc, 0x1000, v64
	s_nop 1
	v_addc_co_u32_e32 v17, vcc, 0, v65, vcc
	global_store_dword v[16:17], v32, off offset:128
.LBB0_1261:
	s_or_b64 exec, exec, s[0:1]
	v_mul_f32_e32 v0, v1, v0
	s_nop 1
	v_mov_b32_dpp v1, v0 quad_perm:[1,0,3,2] row_mask:0xf bank_mask:0xf
	s_and_saveexec_b64 s[0:1], s[4:5]
	s_cbranch_execz .LBB0_1263
	s_waitcnt lgkmcnt(0)
	v_cvt_pk_bf16_f32 v16, v0, v1
	v_add_co_u32_e32 v0, vcc, 0x1000, v64
	s_nop 1
	v_addc_co_u32_e32 v1, vcc, 0, v65, vcc
	global_store_dword v[0:1], v16, off offset:192
.LBB0_1263:
	s_or_b64 exec, exec, s[0:1]
	ds_read_b32 v0, v183 offset:8
	s_waitcnt lgkmcnt(0)
	v_rcp_f32_e32 v0, v0
	s_nop 0
	v_mul_f32_e32 v1, v50, v0
	s_nop 1
	v_mov_b32_dpp v16, v1 quad_perm:[1,0,3,2] row_mask:0xf bank_mask:0xf
	s_and_saveexec_b64 s[0:1], s[4:5]
	s_cbranch_execz .LBB0_1265
	s_waitcnt lgkmcnt(0)
	v_cvt_pk_bf16_f32 v1, v1, v16
	v_add_co_u32_e32 v16, vcc, 0x2000, v64
	s_nop 1
	v_addc_co_u32_e32 v17, vcc, 0, v65, vcc
	global_store_dword v[16:17], v1, off
.LBB0_1265:
	s_or_b64 exec, exec, s[0:1]
	v_mul_f32_e32 v1, v34, v0
	s_waitcnt lgkmcnt(0)
	s_nop 1
	v_mov_b32_dpp v16, v1 quad_perm:[1,0,3,2] row_mask:0xf bank_mask:0xf
	s_and_saveexec_b64 s[0:1], s[4:5]
	s_cbranch_execz .LBB0_1267
	s_waitcnt lgkmcnt(0)
	v_cvt_pk_bf16_f32 v1, v1, v16
	v_add_co_u32_e32 v16, vcc, 0x2000, v64
	s_nop 1
	v_addc_co_u32_e32 v17, vcc, 0, v65, vcc
	global_store_dword v[16:17], v1, off offset:64
.LBB0_1267:
	s_or_b64 exec, exec, s[0:1]
	v_mul_f32_e32 v1, v18, v0
	s_waitcnt lgkmcnt(0)
	s_nop 1
	v_mov_b32_dpp v16, v1 quad_perm:[1,0,3,2] row_mask:0xf bank_mask:0xf
	s_and_saveexec_b64 s[0:1], s[4:5]
	s_cbranch_execz .LBB0_1269
	s_waitcnt lgkmcnt(0)
	v_cvt_pk_bf16_f32 v1, v1, v16
	v_add_co_u32_e32 v16, vcc, 0x2000, v64
	s_nop 1
	v_addc_co_u32_e32 v17, vcc, 0, v65, vcc
	global_store_dword v[16:17], v1, off offset:128
.LBB0_1269:
	s_or_b64 exec, exec, s[0:1]
	v_mul_f32_e32 v0, v2, v0
	s_nop 1
	v_mov_b32_dpp v1, v0 quad_perm:[1,0,3,2] row_mask:0xf bank_mask:0xf
	s_and_saveexec_b64 s[0:1], s[4:5]
	s_cbranch_execz .LBB0_1271
	s_waitcnt lgkmcnt(0)
	v_cvt_pk_bf16_f32 v2, v0, v1
	v_add_co_u32_e32 v0, vcc, 0x2000, v64
	s_nop 1
	v_addc_co_u32_e32 v1, vcc, 0, v65, vcc
	global_store_dword v[0:1], v2, off offset:192
.LBB0_1271:
	s_or_b64 exec, exec, s[0:1]
	ds_read_b32 v0, v183 offset:12
	s_waitcnt lgkmcnt(0)
	v_rcp_f32_e32 v0, v0
	s_nop 0
	v_mul_f32_e32 v1, v51, v0
	s_nop 1
	v_mov_b32_dpp v2, v1 quad_perm:[1,0,3,2] row_mask:0xf bank_mask:0xf
	s_and_saveexec_b64 s[0:1], s[4:5]
	s_cbranch_execz .LBB0_1273
	v_add_co_u32_e32 v16, vcc, 0x3000, v64
	s_waitcnt lgkmcnt(0)
	v_cvt_pk_bf16_f32 v1, v1, v2
	s_nop 0
	v_addc_co_u32_e32 v17, vcc, 0, v65, vcc
	global_store_dword v[16:17], v1, off
.LBB0_1273:
	s_or_b64 exec, exec, s[0:1]
	v_mul_f32_e32 v1, v35, v0
	s_waitcnt lgkmcnt(0)
	s_nop 1
	v_mov_b32_dpp v2, v1 quad_perm:[1,0,3,2] row_mask:0xf bank_mask:0xf
	s_and_saveexec_b64 s[0:1], s[4:5]
	s_cbranch_execz .LBB0_1275
	v_add_co_u32_e32 v16, vcc, 0x3000, v64
	s_waitcnt lgkmcnt(0)
	v_cvt_pk_bf16_f32 v1, v1, v2
	s_nop 0
	v_addc_co_u32_e32 v17, vcc, 0, v65, vcc
	global_store_dword v[16:17], v1, off offset:64
.LBB0_1275:
	s_or_b64 exec, exec, s[0:1]
	v_mul_f32_e32 v1, v19, v0
	s_waitcnt lgkmcnt(0)
	s_nop 1
	v_mov_b32_dpp v2, v1 quad_perm:[1,0,3,2] row_mask:0xf bank_mask:0xf
	s_and_saveexec_b64 s[0:1], s[4:5]
	s_cbranch_execz .LBB0_1277
	v_add_co_u32_e32 v16, vcc, 0x3000, v64
	s_waitcnt lgkmcnt(0)
	v_cvt_pk_bf16_f32 v1, v1, v2
	s_nop 0
	v_addc_co_u32_e32 v17, vcc, 0, v65, vcc
	global_store_dword v[16:17], v1, off offset:128
.LBB0_1277:
	s_or_b64 exec, exec, s[0:1]
	v_mul_f32_e32 v0, v3, v0
	s_nop 1
	v_mov_b32_dpp v1, v0 quad_perm:[1,0,3,2] row_mask:0xf bank_mask:0xf
	s_and_saveexec_b64 s[0:1], s[4:5]
	s_cbranch_execz .LBB0_1279
	s_waitcnt lgkmcnt(0)
	v_cvt_pk_bf16_f32 v2, v0, v1
	v_add_co_u32_e32 v0, vcc, 0x3000, v64
	s_nop 1
	v_addc_co_u32_e32 v1, vcc, 0, v65, vcc
	global_store_dword v[0:1], v2, off offset:192
.LBB0_1279:
	s_or_b64 exec, exec, s[0:1]
	ds_read_b32 v0, v183 offset:32
	s_waitcnt lgkmcnt(0)
	v_rcp_f32_e32 v0, v0
	s_nop 0
	v_mul_f32_e32 v1, v52, v0
	s_nop 1
	v_mov_b32_dpp v2, v1 quad_perm:[1,0,3,2] row_mask:0xf bank_mask:0xf
	s_and_saveexec_b64 s[0:1], s[4:5]
	s_cbranch_execz .LBB0_1281
	s_waitcnt lgkmcnt(0)
	v_cvt_pk_bf16_f32 v1, v1, v2
	v_add_co_u32_e32 v2, vcc, 0x8000, v64
	s_nop 1
	v_addc_co_u32_e32 v3, vcc, 0, v65, vcc
	global_store_dword v[2:3], v1, off
.LBB0_1281:
	s_or_b64 exec, exec, s[0:1]
	v_mul_f32_e32 v1, v36, v0
	s_waitcnt lgkmcnt(0)
	s_nop 1
	v_mov_b32_dpp v2, v1 quad_perm:[1,0,3,2] row_mask:0xf bank_mask:0xf
	s_and_saveexec_b64 s[0:1], s[4:5]
	s_cbranch_execz .LBB0_1283
	s_waitcnt lgkmcnt(0)
	v_cvt_pk_bf16_f32 v1, v1, v2
	v_add_co_u32_e32 v2, vcc, 0x8000, v64
	s_nop 1
	v_addc_co_u32_e32 v3, vcc, 0, v65, vcc
	global_store_dword v[2:3], v1, off offset:64
.LBB0_1283:
	s_or_b64 exec, exec, s[0:1]
	v_mul_f32_e32 v1, v20, v0
	s_waitcnt lgkmcnt(0)
	s_nop 1
	v_mov_b32_dpp v2, v1 quad_perm:[1,0,3,2] row_mask:0xf bank_mask:0xf
	s_and_saveexec_b64 s[0:1], s[4:5]
	s_cbranch_execz .LBB0_1285
	s_waitcnt lgkmcnt(0)
	v_cvt_pk_bf16_f32 v1, v1, v2
	v_add_co_u32_e32 v2, vcc, 0x8000, v64
	s_nop 1
	v_addc_co_u32_e32 v3, vcc, 0, v65, vcc
	global_store_dword v[2:3], v1, off offset:128
.LBB0_1285:
	s_or_b64 exec, exec, s[0:1]
	v_mul_f32_e32 v0, v4, v0
	s_nop 1
	v_mov_b32_dpp v1, v0 quad_perm:[1,0,3,2] row_mask:0xf bank_mask:0xf
	s_and_saveexec_b64 s[0:1], s[4:5]
	s_cbranch_execz .LBB0_1287
	s_waitcnt lgkmcnt(0)
	v_cvt_pk_bf16_f32 v2, v0, v1
	v_add_co_u32_e32 v0, vcc, 0x8000, v64
	s_nop 1
	v_addc_co_u32_e32 v1, vcc, 0, v65, vcc
	global_store_dword v[0:1], v2, off offset:192
.LBB0_1287:
	s_or_b64 exec, exec, s[0:1]
	ds_read_b32 v0, v183 offset:36
	s_waitcnt lgkmcnt(0)
	v_rcp_f32_e32 v0, v0
	s_nop 0
	v_mul_f32_e32 v1, v53, v0
	s_nop 1
	v_mov_b32_dpp v2, v1 quad_perm:[1,0,3,2] row_mask:0xf bank_mask:0xf
	s_and_saveexec_b64 s[0:1], s[4:5]
	s_cbranch_execz .LBB0_1289
	s_waitcnt lgkmcnt(0)
	v_cvt_pk_bf16_f32 v1, v1, v2
	v_add_co_u32_e32 v2, vcc, 0x9000, v64
	s_nop 1
	v_addc_co_u32_e32 v3, vcc, 0, v65, vcc
	global_store_dword v[2:3], v1, off
.LBB0_1289:
	s_or_b64 exec, exec, s[0:1]
	v_mul_f32_e32 v1, v37, v0
	s_waitcnt lgkmcnt(0)
	s_nop 1
	v_mov_b32_dpp v2, v1 quad_perm:[1,0,3,2] row_mask:0xf bank_mask:0xf
	s_and_saveexec_b64 s[0:1], s[4:5]
	s_cbranch_execz .LBB0_1291
	s_waitcnt lgkmcnt(0)
	v_cvt_pk_bf16_f32 v1, v1, v2
	v_add_co_u32_e32 v2, vcc, 0x9000, v64
	s_nop 1
	v_addc_co_u32_e32 v3, vcc, 0, v65, vcc
	global_store_dword v[2:3], v1, off offset:64
.LBB0_1291:
	s_or_b64 exec, exec, s[0:1]
	v_mul_f32_e32 v1, v21, v0
	s_waitcnt lgkmcnt(0)
	s_nop 1
	v_mov_b32_dpp v2, v1 quad_perm:[1,0,3,2] row_mask:0xf bank_mask:0xf
	s_and_saveexec_b64 s[0:1], s[4:5]
	s_cbranch_execz .LBB0_1293
	s_waitcnt lgkmcnt(0)
	v_cvt_pk_bf16_f32 v1, v1, v2
	v_add_co_u32_e32 v2, vcc, 0x9000, v64
	s_nop 1
	v_addc_co_u32_e32 v3, vcc, 0, v65, vcc
	global_store_dword v[2:3], v1, off offset:128
.LBB0_1293:
	s_or_b64 exec, exec, s[0:1]
	v_mul_f32_e32 v0, v5, v0
	s_nop 1
	v_mov_b32_dpp v1, v0 quad_perm:[1,0,3,2] row_mask:0xf bank_mask:0xf
	s_and_saveexec_b64 s[0:1], s[4:5]
	s_cbranch_execz .LBB0_1295
	s_waitcnt lgkmcnt(0)
	v_cvt_pk_bf16_f32 v2, v0, v1
	v_add_co_u32_e32 v0, vcc, 0x9000, v64
	s_nop 1
	v_addc_co_u32_e32 v1, vcc, 0, v65, vcc
	global_store_dword v[0:1], v2, off offset:192
.LBB0_1295:
	s_or_b64 exec, exec, s[0:1]
	ds_read_b32 v0, v183 offset:40
	s_waitcnt lgkmcnt(0)
	v_rcp_f32_e32 v0, v0
	s_nop 0
	v_mul_f32_e32 v1, v54, v0
	s_nop 1
	v_mov_b32_dpp v2, v1 quad_perm:[1,0,3,2] row_mask:0xf bank_mask:0xf
	s_and_saveexec_b64 s[0:1], s[4:5]
	s_cbranch_execz .LBB0_1297
	s_waitcnt lgkmcnt(0)
	v_cvt_pk_bf16_f32 v1, v1, v2
	v_add_co_u32_e32 v2, vcc, 0xa000, v64
	s_nop 1
	v_addc_co_u32_e32 v3, vcc, 0, v65, vcc
	global_store_dword v[2:3], v1, off
.LBB0_1297:
	s_or_b64 exec, exec, s[0:1]
	v_mul_f32_e32 v1, v38, v0
	s_waitcnt lgkmcnt(0)
	s_nop 1
	v_mov_b32_dpp v2, v1 quad_perm:[1,0,3,2] row_mask:0xf bank_mask:0xf
	s_and_saveexec_b64 s[0:1], s[4:5]
	s_cbranch_execz .LBB0_1299
	s_waitcnt lgkmcnt(0)
	v_cvt_pk_bf16_f32 v1, v1, v2
	v_add_co_u32_e32 v2, vcc, 0xa000, v64
	s_nop 1
	v_addc_co_u32_e32 v3, vcc, 0, v65, vcc
	global_store_dword v[2:3], v1, off offset:64
.LBB0_1299:
	s_or_b64 exec, exec, s[0:1]
	v_mul_f32_e32 v1, v22, v0
	s_waitcnt lgkmcnt(0)
	s_nop 1
	v_mov_b32_dpp v2, v1 quad_perm:[1,0,3,2] row_mask:0xf bank_mask:0xf
	s_and_saveexec_b64 s[0:1], s[4:5]
	s_cbranch_execz .LBB0_1301
	s_waitcnt lgkmcnt(0)
	v_cvt_pk_bf16_f32 v1, v1, v2
	v_add_co_u32_e32 v2, vcc, 0xa000, v64
	s_nop 1
	v_addc_co_u32_e32 v3, vcc, 0, v65, vcc
	global_store_dword v[2:3], v1, off offset:128
.LBB0_1301:
	s_or_b64 exec, exec, s[0:1]
	v_mul_f32_e32 v0, v6, v0
	s_nop 1
	v_mov_b32_dpp v1, v0 quad_perm:[1,0,3,2] row_mask:0xf bank_mask:0xf
	s_and_saveexec_b64 s[0:1], s[4:5]
	s_cbranch_execz .LBB0_1303
	s_waitcnt lgkmcnt(0)
	v_cvt_pk_bf16_f32 v2, v0, v1
	v_add_co_u32_e32 v0, vcc, 0xa000, v64
	s_nop 1
	v_addc_co_u32_e32 v1, vcc, 0, v65, vcc
	global_store_dword v[0:1], v2, off offset:192
.LBB0_1303:
	s_or_b64 exec, exec, s[0:1]
	ds_read_b32 v0, v183 offset:44
	s_waitcnt lgkmcnt(0)
	v_rcp_f32_e32 v0, v0
	s_nop 0
	v_mul_f32_e32 v1, v55, v0
	s_nop 1
	v_mov_b32_dpp v2, v1 quad_perm:[1,0,3,2] row_mask:0xf bank_mask:0xf
	s_and_saveexec_b64 s[0:1], s[4:5]
	s_cbranch_execz .LBB0_1305
	s_waitcnt lgkmcnt(0)
	v_cvt_pk_bf16_f32 v1, v1, v2
	v_add_co_u32_e32 v2, vcc, 0xb000, v64
	s_nop 1
	v_addc_co_u32_e32 v3, vcc, 0, v65, vcc
	global_store_dword v[2:3], v1, off
.LBB0_1305:
	s_or_b64 exec, exec, s[0:1]
	v_mul_f32_e32 v1, v39, v0
	s_waitcnt lgkmcnt(0)
	s_nop 1
	v_mov_b32_dpp v2, v1 quad_perm:[1,0,3,2] row_mask:0xf bank_mask:0xf
	s_and_saveexec_b64 s[0:1], s[4:5]
	s_cbranch_execz .LBB0_1307
	s_waitcnt lgkmcnt(0)
	v_cvt_pk_bf16_f32 v1, v1, v2
	v_add_co_u32_e32 v2, vcc, 0xb000, v64
	s_nop 1
	v_addc_co_u32_e32 v3, vcc, 0, v65, vcc
	global_store_dword v[2:3], v1, off offset:64
.LBB0_1307:
	s_or_b64 exec, exec, s[0:1]
	v_mul_f32_e32 v1, v23, v0
	s_waitcnt lgkmcnt(0)
	s_nop 1
	v_mov_b32_dpp v2, v1 quad_perm:[1,0,3,2] row_mask:0xf bank_mask:0xf
	s_and_saveexec_b64 s[0:1], s[4:5]
	s_cbranch_execz .LBB0_1309
	s_waitcnt lgkmcnt(0)
	v_cvt_pk_bf16_f32 v1, v1, v2
	v_add_co_u32_e32 v2, vcc, 0xb000, v64
	s_nop 1
	v_addc_co_u32_e32 v3, vcc, 0, v65, vcc
	global_store_dword v[2:3], v1, off offset:128
.LBB0_1309:
	s_or_b64 exec, exec, s[0:1]
	v_mul_f32_e32 v0, v7, v0
	s_nop 1
	v_mov_b32_dpp v1, v0 quad_perm:[1,0,3,2] row_mask:0xf bank_mask:0xf
	s_and_saveexec_b64 s[0:1], s[4:5]
	s_cbranch_execz .LBB0_1311
	s_waitcnt lgkmcnt(0)
	v_cvt_pk_bf16_f32 v2, v0, v1
	v_add_co_u32_e32 v0, vcc, 0xb000, v64
	s_nop 1
	v_addc_co_u32_e32 v1, vcc, 0, v65, vcc
	global_store_dword v[0:1], v2, off offset:192
.LBB0_1311:
	s_or_b64 exec, exec, s[0:1]
	ds_read_b32 v0, v183 offset:64
	s_waitcnt lgkmcnt(0)
	v_rcp_f32_e32 v0, v0
	s_nop 0
	v_mul_f32_e32 v1, v56, v0
	s_nop 1
	v_mov_b32_dpp v2, v1 quad_perm:[1,0,3,2] row_mask:0xf bank_mask:0xf
	s_and_saveexec_b64 s[0:1], s[4:5]
	s_cbranch_execz .LBB0_1313
	s_waitcnt lgkmcnt(0)
	v_cvt_pk_bf16_f32 v1, v1, v2
	v_add_co_u32_e32 v2, vcc, 0x10000, v64
	s_nop 1
	v_addc_co_u32_e32 v3, vcc, 0, v65, vcc
	global_store_dword v[2:3], v1, off
.LBB0_1313:
	s_or_b64 exec, exec, s[0:1]
	v_mul_f32_e32 v1, v40, v0
	s_waitcnt lgkmcnt(0)
	s_nop 1
	v_mov_b32_dpp v2, v1 quad_perm:[1,0,3,2] row_mask:0xf bank_mask:0xf
	s_and_saveexec_b64 s[0:1], s[4:5]
	s_cbranch_execz .LBB0_1315
	s_waitcnt lgkmcnt(0)
	v_cvt_pk_bf16_f32 v1, v1, v2
	v_add_co_u32_e32 v2, vcc, 0x10000, v64
	s_nop 1
	v_addc_co_u32_e32 v3, vcc, 0, v65, vcc
	global_store_dword v[2:3], v1, off offset:64
.LBB0_1315:
	s_or_b64 exec, exec, s[0:1]
	v_mul_f32_e32 v1, v24, v0
	s_waitcnt lgkmcnt(0)
	s_nop 1
	v_mov_b32_dpp v2, v1 quad_perm:[1,0,3,2] row_mask:0xf bank_mask:0xf
	s_and_saveexec_b64 s[0:1], s[4:5]
	s_cbranch_execz .LBB0_1317
	s_waitcnt lgkmcnt(0)
	v_cvt_pk_bf16_f32 v1, v1, v2
	v_add_co_u32_e32 v2, vcc, 0x10000, v64
	s_nop 1
	v_addc_co_u32_e32 v3, vcc, 0, v65, vcc
	global_store_dword v[2:3], v1, off offset:128
.LBB0_1317:
	s_or_b64 exec, exec, s[0:1]
	v_mul_f32_e32 v0, v8, v0
	s_nop 1
	v_mov_b32_dpp v1, v0 quad_perm:[1,0,3,2] row_mask:0xf bank_mask:0xf
	s_and_saveexec_b64 s[0:1], s[4:5]
	s_cbranch_execz .LBB0_1319
	s_waitcnt lgkmcnt(0)
	v_cvt_pk_bf16_f32 v2, v0, v1
	v_add_co_u32_e32 v0, vcc, 0x10000, v64
	s_nop 1
	v_addc_co_u32_e32 v1, vcc, 0, v65, vcc
	global_store_dword v[0:1], v2, off offset:192
.LBB0_1319:
	s_or_b64 exec, exec, s[0:1]
	ds_read_b32 v0, v183 offset:68
	s_waitcnt lgkmcnt(0)
	v_rcp_f32_e32 v0, v0
	s_nop 0
	v_mul_f32_e32 v1, v57, v0
	s_nop 1
	v_mov_b32_dpp v2, v1 quad_perm:[1,0,3,2] row_mask:0xf bank_mask:0xf
	s_and_saveexec_b64 s[0:1], s[4:5]
	s_cbranch_execz .LBB0_1321
	s_waitcnt lgkmcnt(0)
	v_cvt_pk_bf16_f32 v1, v1, v2
	v_add_co_u32_e32 v2, vcc, 0x11000, v64
	s_nop 1
	v_addc_co_u32_e32 v3, vcc, 0, v65, vcc
	global_store_dword v[2:3], v1, off
.LBB0_1321:
	s_or_b64 exec, exec, s[0:1]
	v_mul_f32_e32 v1, v41, v0
	s_waitcnt lgkmcnt(0)
	s_nop 1
	v_mov_b32_dpp v2, v1 quad_perm:[1,0,3,2] row_mask:0xf bank_mask:0xf
	s_and_saveexec_b64 s[0:1], s[4:5]
	s_cbranch_execz .LBB0_1323
	s_waitcnt lgkmcnt(0)
	v_cvt_pk_bf16_f32 v1, v1, v2
	v_add_co_u32_e32 v2, vcc, 0x11000, v64
	s_nop 1
	v_addc_co_u32_e32 v3, vcc, 0, v65, vcc
	global_store_dword v[2:3], v1, off offset:64
.LBB0_1323:
	s_or_b64 exec, exec, s[0:1]
	v_mul_f32_e32 v1, v25, v0
	s_waitcnt lgkmcnt(0)
	s_nop 1
	v_mov_b32_dpp v2, v1 quad_perm:[1,0,3,2] row_mask:0xf bank_mask:0xf
	s_and_saveexec_b64 s[0:1], s[4:5]
	s_cbranch_execz .LBB0_1325
	s_waitcnt lgkmcnt(0)
	v_cvt_pk_bf16_f32 v1, v1, v2
	v_add_co_u32_e32 v2, vcc, 0x11000, v64
	s_nop 1
	v_addc_co_u32_e32 v3, vcc, 0, v65, vcc
	global_store_dword v[2:3], v1, off offset:128
.LBB0_1325:
	s_or_b64 exec, exec, s[0:1]
	v_mul_f32_e32 v0, v9, v0
	s_nop 1
	v_mov_b32_dpp v1, v0 quad_perm:[1,0,3,2] row_mask:0xf bank_mask:0xf
	s_and_saveexec_b64 s[0:1], s[4:5]
	s_cbranch_execz .LBB0_1327
	s_waitcnt lgkmcnt(0)
	v_cvt_pk_bf16_f32 v2, v0, v1
	v_add_co_u32_e32 v0, vcc, 0x11000, v64
	s_nop 1
	v_addc_co_u32_e32 v1, vcc, 0, v65, vcc
	global_store_dword v[0:1], v2, off offset:192
.LBB0_1327:
	s_or_b64 exec, exec, s[0:1]
	ds_read_b32 v0, v183 offset:72
	s_waitcnt lgkmcnt(0)
	v_rcp_f32_e32 v0, v0
	s_nop 0
	v_mul_f32_e32 v1, v58, v0
	s_nop 1
	v_mov_b32_dpp v2, v1 quad_perm:[1,0,3,2] row_mask:0xf bank_mask:0xf
	s_and_saveexec_b64 s[0:1], s[4:5]
	s_cbranch_execz .LBB0_1329
	s_waitcnt lgkmcnt(0)
	v_cvt_pk_bf16_f32 v1, v1, v2
	v_add_co_u32_e32 v2, vcc, 0x12000, v64
	s_nop 1
	v_addc_co_u32_e32 v3, vcc, 0, v65, vcc
	global_store_dword v[2:3], v1, off
.LBB0_1329:
	s_or_b64 exec, exec, s[0:1]
	v_mul_f32_e32 v1, v42, v0
	s_waitcnt lgkmcnt(0)
	s_nop 1
	v_mov_b32_dpp v2, v1 quad_perm:[1,0,3,2] row_mask:0xf bank_mask:0xf
	s_and_saveexec_b64 s[0:1], s[4:5]
	s_cbranch_execz .LBB0_1331
	s_waitcnt lgkmcnt(0)
	v_cvt_pk_bf16_f32 v1, v1, v2
	v_add_co_u32_e32 v2, vcc, 0x12000, v64
	s_nop 1
	v_addc_co_u32_e32 v3, vcc, 0, v65, vcc
	global_store_dword v[2:3], v1, off offset:64
.LBB0_1331:
	s_or_b64 exec, exec, s[0:1]
	v_mul_f32_e32 v1, v26, v0
	s_waitcnt lgkmcnt(0)
	s_nop 1
	v_mov_b32_dpp v2, v1 quad_perm:[1,0,3,2] row_mask:0xf bank_mask:0xf
	s_and_saveexec_b64 s[0:1], s[4:5]
	s_cbranch_execz .LBB0_1333
	s_waitcnt lgkmcnt(0)
	v_cvt_pk_bf16_f32 v1, v1, v2
	v_add_co_u32_e32 v2, vcc, 0x12000, v64
	s_nop 1
	v_addc_co_u32_e32 v3, vcc, 0, v65, vcc
	global_store_dword v[2:3], v1, off offset:128
.LBB0_1333:
	s_or_b64 exec, exec, s[0:1]
	v_mul_f32_e32 v0, v10, v0
	s_nop 1
	v_mov_b32_dpp v1, v0 quad_perm:[1,0,3,2] row_mask:0xf bank_mask:0xf
	s_and_saveexec_b64 s[0:1], s[4:5]
	s_cbranch_execz .LBB0_1335
	s_waitcnt lgkmcnt(0)
	v_cvt_pk_bf16_f32 v2, v0, v1
	v_add_co_u32_e32 v0, vcc, 0x12000, v64
	s_nop 1
	v_addc_co_u32_e32 v1, vcc, 0, v65, vcc
	global_store_dword v[0:1], v2, off offset:192
.LBB0_1335:
	s_or_b64 exec, exec, s[0:1]
	ds_read_b32 v0, v183 offset:76
	s_waitcnt lgkmcnt(0)
	v_rcp_f32_e32 v0, v0
	s_nop 0
	v_mul_f32_e32 v1, v59, v0
	s_nop 1
	v_mov_b32_dpp v2, v1 quad_perm:[1,0,3,2] row_mask:0xf bank_mask:0xf
	s_and_saveexec_b64 s[0:1], s[4:5]
	s_cbranch_execz .LBB0_1337
	s_waitcnt lgkmcnt(0)
	v_cvt_pk_bf16_f32 v1, v1, v2
	v_add_co_u32_e32 v2, vcc, 0x13000, v64
	s_nop 1
	v_addc_co_u32_e32 v3, vcc, 0, v65, vcc
	global_store_dword v[2:3], v1, off
.LBB0_1337:
	s_or_b64 exec, exec, s[0:1]
	v_mul_f32_e32 v1, v43, v0
	s_waitcnt lgkmcnt(0)
	s_nop 1
	v_mov_b32_dpp v2, v1 quad_perm:[1,0,3,2] row_mask:0xf bank_mask:0xf
	s_and_saveexec_b64 s[0:1], s[4:5]
	s_cbranch_execz .LBB0_1339
	s_waitcnt lgkmcnt(0)
	v_cvt_pk_bf16_f32 v1, v1, v2
	v_add_co_u32_e32 v2, vcc, 0x13000, v64
	s_nop 1
	v_addc_co_u32_e32 v3, vcc, 0, v65, vcc
	global_store_dword v[2:3], v1, off offset:64
.LBB0_1339:
	s_or_b64 exec, exec, s[0:1]
	v_mul_f32_e32 v1, v27, v0
	s_waitcnt lgkmcnt(0)
	s_nop 1
	v_mov_b32_dpp v2, v1 quad_perm:[1,0,3,2] row_mask:0xf bank_mask:0xf
	s_and_saveexec_b64 s[0:1], s[4:5]
	s_cbranch_execz .LBB0_1341
	s_waitcnt lgkmcnt(0)
	v_cvt_pk_bf16_f32 v1, v1, v2
	v_add_co_u32_e32 v2, vcc, 0x13000, v64
	s_nop 1
	v_addc_co_u32_e32 v3, vcc, 0, v65, vcc
	global_store_dword v[2:3], v1, off offset:128
.LBB0_1341:
	s_or_b64 exec, exec, s[0:1]
	v_mul_f32_e32 v0, v11, v0
	s_nop 1
	v_mov_b32_dpp v1, v0 quad_perm:[1,0,3,2] row_mask:0xf bank_mask:0xf
	s_and_saveexec_b64 s[0:1], s[4:5]
	s_cbranch_execz .LBB0_1343
	s_waitcnt lgkmcnt(0)
	v_cvt_pk_bf16_f32 v2, v0, v1
	v_add_co_u32_e32 v0, vcc, 0x13000, v64
	s_nop 1
	v_addc_co_u32_e32 v1, vcc, 0, v65, vcc
	global_store_dword v[0:1], v2, off offset:192
.LBB0_1343:
	s_or_b64 exec, exec, s[0:1]
	ds_read_b32 v0, v183 offset:96
	s_waitcnt lgkmcnt(0)
	v_rcp_f32_e32 v0, v0
	s_nop 0
	v_mul_f32_e32 v1, v60, v0
	s_nop 1
	v_mov_b32_dpp v2, v1 quad_perm:[1,0,3,2] row_mask:0xf bank_mask:0xf
	s_and_saveexec_b64 s[0:1], s[4:5]
	s_cbranch_execz .LBB0_1345
	s_waitcnt lgkmcnt(0)
	v_cvt_pk_bf16_f32 v1, v1, v2
	v_add_co_u32_e32 v2, vcc, 0x18000, v64
	s_nop 1
	v_addc_co_u32_e32 v3, vcc, 0, v65, vcc
	global_store_dword v[2:3], v1, off
.LBB0_1345:
	s_or_b64 exec, exec, s[0:1]
	v_mul_f32_e32 v1, v44, v0
	s_waitcnt lgkmcnt(0)
	s_nop 1
	v_mov_b32_dpp v2, v1 quad_perm:[1,0,3,2] row_mask:0xf bank_mask:0xf
	s_and_saveexec_b64 s[0:1], s[4:5]
	s_cbranch_execz .LBB0_1347
	s_waitcnt lgkmcnt(0)
	v_cvt_pk_bf16_f32 v1, v1, v2
	v_add_co_u32_e32 v2, vcc, 0x18000, v64
	s_nop 1
	v_addc_co_u32_e32 v3, vcc, 0, v65, vcc
	global_store_dword v[2:3], v1, off offset:64
.LBB0_1347:
	s_or_b64 exec, exec, s[0:1]
	v_mul_f32_e32 v1, v28, v0
	s_waitcnt lgkmcnt(0)
	s_nop 1
	v_mov_b32_dpp v2, v1 quad_perm:[1,0,3,2] row_mask:0xf bank_mask:0xf
	s_and_saveexec_b64 s[0:1], s[4:5]
	s_cbranch_execz .LBB0_1349
	s_waitcnt lgkmcnt(0)
	v_cvt_pk_bf16_f32 v1, v1, v2
	v_add_co_u32_e32 v2, vcc, 0x18000, v64
	s_nop 1
	v_addc_co_u32_e32 v3, vcc, 0, v65, vcc
	global_store_dword v[2:3], v1, off offset:128
.LBB0_1349:
	s_or_b64 exec, exec, s[0:1]
	v_mul_f32_e32 v0, v12, v0
	s_nop 1
	v_mov_b32_dpp v1, v0 quad_perm:[1,0,3,2] row_mask:0xf bank_mask:0xf
	s_and_saveexec_b64 s[0:1], s[4:5]
	s_cbranch_execz .LBB0_1351
	s_waitcnt lgkmcnt(0)
	v_cvt_pk_bf16_f32 v2, v0, v1
	v_add_co_u32_e32 v0, vcc, 0x18000, v64
	s_nop 1
	v_addc_co_u32_e32 v1, vcc, 0, v65, vcc
	global_store_dword v[0:1], v2, off offset:192
.LBB0_1351:
	s_or_b64 exec, exec, s[0:1]
	ds_read_b32 v0, v183 offset:100
	s_waitcnt lgkmcnt(0)
	v_rcp_f32_e32 v0, v0
	s_nop 0
	v_mul_f32_e32 v1, v61, v0
	s_nop 1
	v_mov_b32_dpp v2, v1 quad_perm:[1,0,3,2] row_mask:0xf bank_mask:0xf
	s_and_saveexec_b64 s[0:1], s[4:5]
	s_cbranch_execz .LBB0_1353
	s_waitcnt lgkmcnt(0)
	v_cvt_pk_bf16_f32 v1, v1, v2
	v_add_co_u32_e32 v2, vcc, 0x19000, v64
	s_nop 1
	v_addc_co_u32_e32 v3, vcc, 0, v65, vcc
	global_store_dword v[2:3], v1, off
.LBB0_1353:
	s_or_b64 exec, exec, s[0:1]
	v_mul_f32_e32 v1, v45, v0
	s_waitcnt lgkmcnt(0)
	s_nop 1
	v_mov_b32_dpp v2, v1 quad_perm:[1,0,3,2] row_mask:0xf bank_mask:0xf
	s_and_saveexec_b64 s[0:1], s[4:5]
	s_cbranch_execz .LBB0_1355
	s_waitcnt lgkmcnt(0)
	v_cvt_pk_bf16_f32 v1, v1, v2
	v_add_co_u32_e32 v2, vcc, 0x19000, v64
	s_nop 1
	v_addc_co_u32_e32 v3, vcc, 0, v65, vcc
	global_store_dword v[2:3], v1, off offset:64
.LBB0_1355:
	s_or_b64 exec, exec, s[0:1]
	v_mul_f32_e32 v1, v29, v0
	s_waitcnt lgkmcnt(0)
	s_nop 1
	v_mov_b32_dpp v2, v1 quad_perm:[1,0,3,2] row_mask:0xf bank_mask:0xf
	s_and_saveexec_b64 s[0:1], s[4:5]
	s_cbranch_execz .LBB0_1357
	s_waitcnt lgkmcnt(0)
	v_cvt_pk_bf16_f32 v1, v1, v2
	v_add_co_u32_e32 v2, vcc, 0x19000, v64
	s_nop 1
	v_addc_co_u32_e32 v3, vcc, 0, v65, vcc
	global_store_dword v[2:3], v1, off offset:128
.LBB0_1357:
	s_or_b64 exec, exec, s[0:1]
	v_mul_f32_e32 v0, v13, v0
	s_nop 1
	v_mov_b32_dpp v1, v0 quad_perm:[1,0,3,2] row_mask:0xf bank_mask:0xf
	s_and_saveexec_b64 s[0:1], s[4:5]
	s_cbranch_execz .LBB0_1359
	s_waitcnt lgkmcnt(0)
	v_cvt_pk_bf16_f32 v2, v0, v1
	v_add_co_u32_e32 v0, vcc, 0x19000, v64
	s_nop 1
	v_addc_co_u32_e32 v1, vcc, 0, v65, vcc
	global_store_dword v[0:1], v2, off offset:192
.LBB0_1359:
	s_or_b64 exec, exec, s[0:1]
	ds_read_b32 v0, v183 offset:104
	s_waitcnt lgkmcnt(0)
	v_rcp_f32_e32 v0, v0
	s_nop 0
	v_mul_f32_e32 v1, v62, v0
	s_nop 1
	v_mov_b32_dpp v2, v1 quad_perm:[1,0,3,2] row_mask:0xf bank_mask:0xf
	s_and_saveexec_b64 s[0:1], s[4:5]
	s_cbranch_execz .LBB0_1361
	s_waitcnt lgkmcnt(0)
	v_cvt_pk_bf16_f32 v1, v1, v2
	v_add_co_u32_e32 v2, vcc, 0x1a000, v64
	s_nop 1
	v_addc_co_u32_e32 v3, vcc, 0, v65, vcc
	global_store_dword v[2:3], v1, off
.LBB0_1361:
	s_or_b64 exec, exec, s[0:1]
	v_mul_f32_e32 v1, v46, v0
	s_waitcnt lgkmcnt(0)
	s_nop 1
	v_mov_b32_dpp v2, v1 quad_perm:[1,0,3,2] row_mask:0xf bank_mask:0xf
	s_and_saveexec_b64 s[0:1], s[4:5]
	s_cbranch_execz .LBB0_1363
	s_waitcnt lgkmcnt(0)
	v_cvt_pk_bf16_f32 v1, v1, v2
	v_add_co_u32_e32 v2, vcc, 0x1a000, v64
	s_nop 1
	v_addc_co_u32_e32 v3, vcc, 0, v65, vcc
	global_store_dword v[2:3], v1, off offset:64
.LBB0_1363:
	s_or_b64 exec, exec, s[0:1]
	v_mul_f32_e32 v1, v30, v0
	s_waitcnt lgkmcnt(0)
	s_nop 1
	v_mov_b32_dpp v2, v1 quad_perm:[1,0,3,2] row_mask:0xf bank_mask:0xf
	s_and_saveexec_b64 s[0:1], s[4:5]
	s_cbranch_execz .LBB0_1365
	s_waitcnt lgkmcnt(0)
	v_cvt_pk_bf16_f32 v1, v1, v2
	v_add_co_u32_e32 v2, vcc, 0x1a000, v64
	s_nop 1
	v_addc_co_u32_e32 v3, vcc, 0, v65, vcc
	global_store_dword v[2:3], v1, off offset:128
.LBB0_1365:
	s_or_b64 exec, exec, s[0:1]
	v_mul_f32_e32 v0, v14, v0
	s_nop 1
	v_mov_b32_dpp v1, v0 quad_perm:[1,0,3,2] row_mask:0xf bank_mask:0xf
	s_and_saveexec_b64 s[0:1], s[4:5]
	s_cbranch_execz .LBB0_1367
	s_waitcnt lgkmcnt(0)
	v_cvt_pk_bf16_f32 v2, v0, v1
	v_add_co_u32_e32 v0, vcc, 0x1a000, v64
	s_nop 1
	v_addc_co_u32_e32 v1, vcc, 0, v65, vcc
	global_store_dword v[0:1], v2, off offset:192
.LBB0_1367:
	s_or_b64 exec, exec, s[0:1]
	ds_read_b32 v0, v183 offset:108
	s_waitcnt lgkmcnt(0)
	v_rcp_f32_e32 v0, v0
	s_nop 0
	v_mul_f32_e32 v1, v63, v0
	s_nop 1
	v_mov_b32_dpp v2, v1 quad_perm:[1,0,3,2] row_mask:0xf bank_mask:0xf
	s_and_saveexec_b64 s[0:1], s[4:5]
	s_cbranch_execz .LBB0_1369
	s_waitcnt lgkmcnt(0)
	v_cvt_pk_bf16_f32 v1, v1, v2
	v_add_co_u32_e32 v2, vcc, 0x1b000, v64
	s_nop 1
	v_addc_co_u32_e32 v3, vcc, 0, v65, vcc
	global_store_dword v[2:3], v1, off
.LBB0_1369:
	s_or_b64 exec, exec, s[0:1]
	v_mul_f32_e32 v1, v47, v0
	s_waitcnt lgkmcnt(0)
	s_nop 1
	v_mov_b32_dpp v2, v1 quad_perm:[1,0,3,2] row_mask:0xf bank_mask:0xf
	s_and_saveexec_b64 s[0:1], s[4:5]
	s_cbranch_execz .LBB0_1371
	s_waitcnt lgkmcnt(0)
	v_cvt_pk_bf16_f32 v1, v1, v2
	v_add_co_u32_e32 v2, vcc, 0x1b000, v64
	s_nop 1
	v_addc_co_u32_e32 v3, vcc, 0, v65, vcc
	global_store_dword v[2:3], v1, off offset:64
.LBB0_1371:
	s_or_b64 exec, exec, s[0:1]
	v_mul_f32_e32 v1, v31, v0
	s_waitcnt lgkmcnt(0)
	s_nop 1
	v_mov_b32_dpp v2, v1 quad_perm:[1,0,3,2] row_mask:0xf bank_mask:0xf
	s_and_saveexec_b64 s[0:1], s[4:5]
	s_cbranch_execz .LBB0_1373
	s_waitcnt lgkmcnt(0)
	v_cvt_pk_bf16_f32 v1, v1, v2
	v_add_co_u32_e32 v2, vcc, 0x1b000, v64
	s_nop 1
	v_addc_co_u32_e32 v3, vcc, 0, v65, vcc
	global_store_dword v[2:3], v1, off offset:128
.LBB0_1373:
	s_or_b64 exec, exec, s[0:1]
	v_mul_f32_e32 v0, v15, v0
	s_nop 1
	v_mov_b32_dpp v1, v0 quad_perm:[1,0,3,2] row_mask:0xf bank_mask:0xf
	s_and_saveexec_b64 s[0:1], s[4:5]
	s_cbranch_execnz .LBB0_1375
	s_or_b64 exec, exec, s[0:1]
	s_andn2_b64 vcc, exec, s[82:83]
	s_cbranch_vccnz .LBB0_1171
	s_branch .LBB0_1376
